# workgroups without carry work do not wait at the barrier in front of the carry phase
# speedup vs baseline: 1.0457x; 1.0004x over previous
; __device__ __forceinline__ unsigned xb_ld(unsigned* p)              { return __hip_atomic_load(p, __ATOMIC_RELAXED, __HIP_MEMORY_SCOPE_AGENT); }
; __device__ __forceinline__ unsigned xb_add(unsigned* p, unsigned v) { return __hip_atomic_fetch_add(p, v, __ATOMIC_RELAXED, __HIP_MEMORY_SCOPE_AGENT); }
; #define XB_SPIN(cond, bar) do { unsigned _sp = 0; while (cond) { __builtin_amdgcn_s_sleep(1); \
;     if ((++_sp & 255u) == 0u) { if (xb_ld(&(bar)[XB_TMO])) break; if (_sp > XB_SPIN_CAP) { atomicAdd(&(bar)[XB_TMO], 1u); break; } } } } while (0)
; __device__ __forceinline__ void xcd_barrier(const XcdBarrier& b) {
;     ...
;         const unsigned old = xb_add(&bar[XB_XSUB(b.x)], 1u);
;         const unsigned gen = old / nloc;
;         if (old + 1u == (gen + 1u) * nloc) {
;             __builtin_amdgcn_fence(__ATOMIC_RELEASE, "agent");
;             asm volatile("s_waitcnt vmcnt(0)" ::: "memory");
;             const unsigned og = xb_add(&bar[XB_TOP], 1u);
;             const unsigned tg = og / nx;
;             if (og + 1u == (tg + 1u) * nx) xb_add(&bar[XB_TOPGEN], 1u);
;             else XB_SPIN(xb_ld(&bar[XB_TOPGEN]) == tg, bar);
;             __builtin_amdgcn_fence(__ATOMIC_ACQUIRE, "agent");
;             xb_add(&bar[XB_XGEN(b.x)], 1u);
;             asm volatile("s_waitcnt vmcnt(0)" ::: "memory");
;         } else {
;             XB_SPIN(xb_ld(&bar[XB_XGEN(b.x)]) == gen, bar);
.LBB0_1165:
	global_atomic_add v4, v[150:151], v176, off sc0
	v_cvt_f32_u32_e32 v0, v3
	v_sub_u32_e32 v5, 0, v3
	v_rcp_iflag_f32_e32 v0, v0
	s_nop 0
	v_mul_f32_e32 v0, 0x4f7ffffe, v0
	v_cvt_u32_f32_e32 v0, v0
	v_mul_lo_u32 v5, v5, v0
	v_mul_hi_u32 v5, v0, v5
	v_add_u32_e32 v0, v0, v5
	s_waitcnt vmcnt(0)
	v_mul_hi_u32 v0, v4, v0
	v_mul_lo_u32 v5, v0, v3
	v_sub_u32_e32 v5, v4, v5
	v_add_u32_e32 v6, 1, v0
	v_cmp_ge_u32_e32 vcc, v5, v3
	v_add_u32_e32 v4, 1, v4
	s_nop 0
	v_cndmask_b32_e32 v0, v0, v6, vcc
	v_sub_u32_e32 v6, v5, v3
	v_cndmask_b32_e32 v5, v5, v6, vcc
	v_add_u32_e32 v6, 1, v0
	v_cmp_ge_u32_e32 vcc, v5, v3
	s_nop 1
	v_cndmask_b32_e32 v0, v0, v6, vcc
	v_mul_lo_u32 v5, v3, v0
	v_add_u32_e32 v3, v5, v3
	v_cmp_ne_u32_e32 vcc, v4, v3
	s_and_saveexec_b64 s[6:7], vcc
	s_xor_b64 s[6:7], exec, s[6:7]
	s_cbranch_execz .LBB0_1179
	v_readlane_b32 s5, v228, 16
	s_cmp_lg_u32 s5, 0
	s_cbranch_scc0 .LBB0_1179
	s_waitcnt lgkmcnt(0)
	global_load_dword v2, v[148:149], off sc1
	s_waitcnt vmcnt(0)
	v_cmp_eq_u32_e32 vcc, v2, v0
	s_and_saveexec_b64 s[24:25], vcc
	s_cbranch_execz .LBB0_1178
	s_mov_b32 s5, 1
	s_mov_b64 s[26:27], 0
	s_branch .LBB0_1169
